# gate-up->down grid barrier also replaced by the 4-workgroup sync; converting workgroups publish next-layer weights themselves (wbl2 + counter), awaited at down->in-proj
# speedup vs baseline: 1.0217x; 1.0024x over previous
.LBB0_1037:
	s_mul_i32 s0, s31, 5
	s_lshr_b32 s0, s30, s0
	s_bfe_u32 s26, s0, 0x30002
	s_lshl_b32 s0, s0, 5
	s_and_b32 s0, s0, 0x60
	v_readlane_b32 s1, v254, 22
	s_or_b32 s4, s0, s1
	s_cmp_gt_u32 s4, 47
	s_mov_b64 s[0:1], -1
	s_cbranch_scc0 .LBB0_1053
	s_add_i32 s5, s96, 1
	s_cmp_eq_u32 s100, s5
	s_cbranch_scc1 .Lidw_skip
	s_mov_b32 s100, s5
	v_readlane_b32 s0, v252, 5
	s_nop 0
	s_cmp_lg_u32 s0, 0
	s_cbranch_scc1 .Lidw_others
	s_add_u32 s0, s40, 0x13503408
	s_addc_u32 s1, s41, 0
	s_lshl_b32 s5, s5, 8
	v_mov_b32_e32 v1, s5
	buffer_inv sc1
	s_mov_b32 s5, 0

.LgA_have:
	s_cmp_eq_u32 s32, 1
	s_cbranch_scc0 .LgA_orig
	v_readlane_b32 s4, v252, 0
	s_nop 0
	s_and_b32 s4, s4, 63
	s_lshl_b32 s4, s4, 2
	s_add_u32 s4, s4, 0x13500000
	s_add_u32 s4, s40, s4
	s_addc_u32 s5, s41, 0
	v_mov_b32_e32 v1, 1
	s_mov_b64 exec, 1
	global_atomic_add v65, v1, s[4:5]
	buffer_inv sc1
	s_mul_i32 s6, s96, 12
	s_add_i32 s6, s6, 4
	v_mov_b32_e32 v2, s6
	s_mov_b32 s27, 0

.LBB0_1606:
	v_readlane_b32 s0, v255, 8
	s_add_i32 s26, s0, 7
	s_cmp_ge_i32 s26, s93
	s_cbranch_scc1 .LBB0_1662
	s_waitcnt vmcnt(0)
	v_readlane_b32 s0, v252, 3
	v_readlane_b32 s1, v252, 4
	s_and_b64 vcc, exec, s[0:1]
	s_waitcnt lgkmcnt(0)
	s_barrier
	s_cbranch_vccnz .LBB0_1661
	s_cmp_eq_u32 s32, 1
	s_cbranch_scc0 .LgM_orig
	v_readlane_b32 s4, v252, 0
	s_nop 0
	s_and_b32 s4, s4, 63
	s_lshl_b32 s4, s4, 2
	s_add_u32 s4, s4, 0x13500000
	s_add_u32 s4, s40, s4
	s_addc_u32 s5, s41, 0
	v_mov_b32_e32 v1, 1
	s_mov_b64 exec, 1
	global_atomic_add v65, v1, s[4:5]
	buffer_inv sc1
	s_cmp_gt_u32 s96, 2
	s_cbranch_scc1 .LgM_nc
	v_readlane_b32 s27, v252, 0
	s_nop 0
	s_cmp_lt_u32 s27, 0x80
	s_cbranch_scc1 .LgM_nc
	buffer_wbl2 sc1
	s_waitcnt vmcnt(0)
	s_add_u32 s4, s40, 0x1350340c
	s_addc_u32 s5, s41, 0
	global_atomic_add v65, v1, s[4:5]
	s_mov_b64 exec, -1
	v_readlane_b32 s4, v252, 0
	s_nop 0
	s_and_b32 s4, s4, 63
	s_lshl_b32 s4, s4, 2
	s_add_u32 s4, s4, 0x13500000
	s_add_u32 s4, s40, s4
	s_addc_u32 s5, s41, 0
	s_mov_b64 exec, 1
.LgM_nc:
	s_mul_i32 s6, s96, 12
	s_add_i32 s6, s6, 8
	v_mov_b32_e32 v2, s6
	s_mov_b32 s27, 0

.LBB0_1662:
	s_nop 0
	s_cmp_ge_i32 s26, s92
	s_cselect_b64 s[0:1], -1, 0
	s_cmp_lt_i32 s26, s93
	s_cselect_b64 s[4:5], -1, 0
	s_and_b64 s[0:1], s[0:1], s[4:5]
	s_andn2_b64 vcc, exec, s[0:1]
	s_cbranch_vccz .LBB0_1663
	s_getpc_b64 s[98:99]

.LBB0_1739:
	s_cmp_eq_u32 s32, 1
	s_cbranch_scc0 .LgB_orig
	v_readlane_b32 s4, v252, 0
	s_nop 0
	s_and_b32 s4, s4, 63
	s_lshl_b32 s4, s4, 2
	s_add_u32 s4, s4, 0x13500000
	s_add_u32 s4, s40, s4
	s_addc_u32 s5, s41, 0
	v_mov_b32_e32 v1, 1
	s_mov_b64 exec, 1
	global_atomic_add v65, v1, s[4:5]
	buffer_inv sc1
	s_mul_i32 s6, s96, 12
	s_add_i32 s6, s6, 12
	v_mov_b32_e32 v2, s6
	s_mov_b32 s27, 0

.LgB_done:
	s_add_u32 s4, s40, 0x1350340c
	s_addc_u32 s5, s41, 0
	s_add_i32 s6, s96, 1
	s_lshl_b32 s6, s6, 7
	v_mov_b32_e32 v2, s6
	s_mov_b32 s27, 0
